# stack + MERGE epilogue specialised on last-segment flag (fin path multiplies by gate directly; non-fin drops select)
# speedup vs baseline: 1.0212x; 1.0002x over previous
.LBB0_1080:
	s_lshl_b32 s34, s7, 10
	s_ashr_i32 s35, s34, 31
	s_add_i32 s21, s34, 0x400
	v_mbcnt_lo_u32_b32 v144, -1, 0
	v_mbcnt_hi_u32_b32 v144, -1, v144
	s_cmp_eq_u32 s7, 2
	s_cselect_b64 s[30:31], -1, 0
	s_and_b64 s[36:37], s[30:31], exec
	v_and_or_b32 v145, v144, 15, s33
	v_ashrrev_i32_e32 v144, 1, v144
	s_cselect_b32 s36, 0x800, s21
	s_lshl_b32 s6, s6, 8
	v_and_b32_e32 v147, -8, v144
	v_lshl_add_u32 v146, s64, 8, v145
	v_mov_b64_e32 v[144:145], s[8:9]
	s_or_b32 s6, s6, s40
	v_mad_i64_i32 v[144:145], s[38:39], v146, s85, v[144:145]
	v_lshl_add_u64 v[150:151], v[144:145], 0, s[88:89]
	v_add_u32_e32 v144, s6, v147
	v_ashrrev_i32_e32 v145, 31, v144
	s_ashr_i32 s37, s36, 31
	v_lshl_add_u64 v[152:153], s[34:35], 1, v[150:151]
	v_lshlrev_b64 v[148:149], 1, v[144:145]
	v_lshl_add_u64 v[150:151], s[36:37], 1, v[150:151]
	v_lshl_add_u64 v[152:153], v[152:153], 0, v[148:149]
	v_lshl_add_u64 v[154:155], v[150:151], 0, v[148:149]
	s_cmp_lg_u64 s[30:31], 0
	s_cbranch_scc1 .Lmrg_fin_A
	global_load_dwordx4 v[158:161], v[152:153], off
	global_load_dwordx4 v[162:165], v[154:155], off
	global_load_dwordx4 v[176:179], v[152:153], off offset:256
	global_load_dwordx4 v[180:183], v[154:155], off offset:256
	v_ashrrev_i32_e32 v147, 31, v146
	v_lshlrev_b64 v[150:151], 11, v[146:147]
	v_lshl_add_u64 v[150:151], s[10:11], 0, v[150:151]
	s_cmp_lg_u32 s7, 2
	s_waitcnt vmcnt(2)
	v_lshlrev_b32_e32 v147, 16, v158
	v_and_b32_e32 v166, 0xffff0000, v158
	v_lshlrev_b32_e32 v167, 16, v159
	v_and_b32_e32 v168, 0xffff0000, v159
	v_lshlrev_b32_e32 v158, 16, v162
	v_and_b32_e32 v159, 0xffff0000, v162
	v_lshlrev_b32_e32 v162, 16, v163
	v_and_b32_e32 v163, 0xffff0000, v163
	v_lshlrev_b32_e32 v169, 16, v160
	v_and_b32_e32 v170, 0xffff0000, v160
	v_lshlrev_b32_e32 v171, 16, v161
	v_and_b32_e32 v172, 0xffff0000, v161
	v_lshlrev_b32_e32 v160, 16, v164
	v_and_b32_e32 v161, 0xffff0000, v164
	v_lshlrev_b32_e32 v164, 16, v165
	v_and_b32_e32 v165, 0xffff0000, v165
	v_max_f32_e32 v158, 0x1e3ce508, v158
	v_max_f32_e32 v159, 0x1e3ce508, v159
	v_max_f32_e32 v162, 0x1e3ce508, v162
	v_max_f32_e32 v163, 0x1e3ce508, v163
	v_max_f32_e32 v160, 0x1e3ce508, v160
	v_max_f32_e32 v161, 0x1e3ce508, v161
	v_max_f32_e32 v164, 0x1e3ce508, v164
	v_max_f32_e32 v165, 0x1e3ce508, v165
	v_rcp_f32_e32 v158, v158
	v_rcp_f32_e32 v159, v159
	v_rcp_f32_e32 v162, v162
	v_rcp_f32_e32 v163, v163
	v_rcp_f32_e32 v160, v160
	v_rcp_f32_e32 v161, v161
	v_rcp_f32_e32 v164, v164
	v_rcp_f32_e32 v165, v165
	v_mov_b32_e32 v173, v160
	v_mov_b32_e32 v174, v161
	v_mul_f32_e32 v158, v158, v147
	v_mul_f32_e32 v159, v159, v166
	v_mul_f32_e32 v160, v162, v167
	v_mul_f32_e32 v161, v163, v168
	v_mul_f32_e32 v162, v173, v169
	v_mul_f32_e32 v163, v174, v170
	v_mul_f32_e32 v164, v164, v171
	v_mul_f32_e32 v165, v165, v172
	v_pk_mul_f32 v[112:113], v[112:113], v[160:161]
	v_pk_mul_f32 v[110:111], v[110:111], v[158:159]
	v_pk_mul_f32 v[108:109], v[108:109], v[164:165]
	v_pk_mul_f32 v[106:107], v[106:107], v[162:163]
	s_waitcnt vmcnt(0)
	s_cbranch_scc1 .LBB0_1082
	v_lshl_add_u64 v[162:163], v[144:145], 1, v[150:151]
	v_cvt_pk_bf16_f32 v158, v110, v111
	v_cvt_pk_bf16_f32 v159, v112, v113
	v_cvt_pk_bf16_f32 v160, v106, v107
	v_cvt_pk_bf16_f32 v161, v108, v109
	global_store_dwordx4 v[162:163], v[158:161], off
.LBB0_1082:
	v_cndmask_b32_e64 v147, 0, 1, s[30:31]
	v_cmp_ne_u32_e64 s[6:7], 1, v147
	s_andn2_b64 vcc, exec, s[30:31]
	v_lshlrev_b32_e32 v147, 16, v176
	v_lshlrev_b32_e32 v163, 16, v180
	v_and_b32_e32 v180, 0xffff0000, v180
	v_lshlrev_b32_e32 v164, 16, v181
	v_and_b32_e32 v181, 0xffff0000, v181
	v_lshlrev_b32_e32 v167, 16, v182
	v_and_b32_e32 v182, 0xffff0000, v182
	v_lshlrev_b32_e32 v168, 16, v183
	v_and_b32_e32 v183, 0xffff0000, v183
	v_max_f32_e32 v163, 0x1e3ce508, v163
	v_max_f32_e32 v180, 0x1e3ce508, v180
	v_max_f32_e32 v164, 0x1e3ce508, v164
	v_max_f32_e32 v181, 0x1e3ce508, v181
	v_max_f32_e32 v167, 0x1e3ce508, v167
	v_max_f32_e32 v182, 0x1e3ce508, v182
	v_max_f32_e32 v168, 0x1e3ce508, v168
	v_max_f32_e32 v183, 0x1e3ce508, v183
	v_rcp_f32_e32 v163, v163
	v_rcp_f32_e32 v180, v180
	v_rcp_f32_e32 v164, v164
	v_rcp_f32_e32 v181, v181
	v_rcp_f32_e32 v167, v167
	v_rcp_f32_e32 v182, v182
	v_rcp_f32_e32 v168, v168
	v_rcp_f32_e32 v183, v183
	v_and_b32_e32 v176, 0xffff0000, v176
	v_lshlrev_b32_e32 v162, 16, v177
	v_and_b32_e32 v177, 0xffff0000, v177
	v_lshlrev_b32_e32 v165, 16, v178
	v_and_b32_e32 v178, 0xffff0000, v178
	v_lshlrev_b32_e32 v166, 16, v179
	v_and_b32_e32 v179, 0xffff0000, v179
	v_mov_b32_e32 v169, v180
	v_mov_b32_e32 v170, v181
	v_mov_b32_e32 v171, v182
	v_mov_b32_e32 v172, v183
	v_mul_f32_e32 v180, v163, v147
	v_mul_f32_e32 v181, v169, v176
	v_mul_f32_e32 v182, v164, v162
	v_mul_f32_e32 v183, v170, v177
	v_mul_f32_e32 v176, v167, v165
	v_mul_f32_e32 v177, v171, v178
	v_mul_f32_e32 v178, v168, v166
	v_mul_f32_e32 v179, v172, v179
	v_pk_mul_f32 v[80:81], v[80:81], v[182:183]
	v_pk_mul_f32 v[78:79], v[78:79], v[180:181]
	v_pk_mul_f32 v[76:77], v[76:77], v[178:179]
	v_pk_mul_f32 v[74:75], v[74:75], v[176:177]
	s_cbranch_vccnz .LBB0_1084
	v_lshl_add_u64 v[150:151], v[144:145], 1, v[150:151]
	v_cvt_pk_bf16_f32 v180, v78, v79
	v_cvt_pk_bf16_f32 v181, v80, v81
	v_cvt_pk_bf16_f32 v182, v74, v75
	v_cvt_pk_bf16_f32 v183, v76, v77
	global_store_dwordx4 v[150:151], v[180:183], off offset:256
.LBB0_1084:
	v_or_b32_e32 v150, 16, v146
	s_nop 0
	v_mov_b64_e32 v[152:153], s[8:9]
	v_mad_i64_i32 v[152:153], s[38:39], v150, s85, v[152:153]
	v_lshl_add_u64 v[154:155], v[152:153], 0, s[88:89]
	v_lshl_add_u64 v[152:153], s[34:35], 1, v[154:155]
	v_lshl_add_u64 v[154:155], s[36:37], 1, v[154:155]
	v_lshl_add_u64 v[152:153], v[152:153], 0, v[148:149]
	v_lshl_add_u64 v[154:155], v[154:155], 0, v[148:149]
	global_load_dwordx4 v[158:161], v[152:153], off
	global_load_dwordx4 v[162:165], v[154:155], off
	global_load_dwordx4 v[176:179], v[152:153], off offset:256
	global_load_dwordx4 v[180:183], v[154:155], off offset:256
	v_ashrrev_i32_e32 v151, 31, v150
	v_lshlrev_b64 v[150:151], 11, v[150:151]
	s_and_b64 vcc, exec, s[6:7]
	v_lshl_add_u64 v[150:151], s[10:11], 0, v[150:151]
	s_waitcnt vmcnt(3)
	v_lshlrev_b32_e32 v147, 16, v158
	v_and_b32_e32 v166, 0xffff0000, v158
	v_lshlrev_b32_e32 v167, 16, v159
	v_and_b32_e32 v168, 0xffff0000, v159
	s_waitcnt vmcnt(2)
	v_lshlrev_b32_e32 v158, 16, v162
	v_and_b32_e32 v159, 0xffff0000, v162
	v_lshlrev_b32_e32 v162, 16, v163
	v_and_b32_e32 v163, 0xffff0000, v163
	v_lshlrev_b32_e32 v169, 16, v160
	v_and_b32_e32 v170, 0xffff0000, v160
	v_lshlrev_b32_e32 v171, 16, v161
	v_and_b32_e32 v172, 0xffff0000, v161
	v_lshlrev_b32_e32 v160, 16, v164
	v_and_b32_e32 v161, 0xffff0000, v164
	v_lshlrev_b32_e32 v164, 16, v165
	v_and_b32_e32 v165, 0xffff0000, v165
	v_max_f32_e32 v158, 0x1e3ce508, v158
	v_max_f32_e32 v159, 0x1e3ce508, v159
	v_max_f32_e32 v162, 0x1e3ce508, v162
	v_max_f32_e32 v163, 0x1e3ce508, v163
	v_max_f32_e32 v160, 0x1e3ce508, v160
	v_max_f32_e32 v161, 0x1e3ce508, v161
	v_max_f32_e32 v164, 0x1e3ce508, v164
	v_max_f32_e32 v165, 0x1e3ce508, v165
	v_rcp_f32_e32 v158, v158
	v_rcp_f32_e32 v159, v159
	v_rcp_f32_e32 v162, v162
	v_rcp_f32_e32 v163, v163
	v_rcp_f32_e32 v160, v160
	v_rcp_f32_e32 v161, v161
	v_rcp_f32_e32 v164, v164
	v_rcp_f32_e32 v165, v165
	v_mov_b32_e32 v173, v160
	v_mov_b32_e32 v174, v161
	v_mul_f32_e32 v158, v158, v147
	v_mul_f32_e32 v159, v159, v166
	v_mul_f32_e32 v160, v162, v167
	v_mul_f32_e32 v161, v163, v168
	v_mul_f32_e32 v162, v173, v169
	v_mul_f32_e32 v163, v174, v170
	v_mul_f32_e32 v164, v164, v171
	v_mul_f32_e32 v165, v165, v172
	v_pk_mul_f32 v[104:105], v[104:105], v[160:161]
	v_pk_mul_f32 v[102:103], v[102:103], v[158:159]
	v_pk_mul_f32 v[100:101], v[100:101], v[164:165]
	v_pk_mul_f32 v[98:99], v[98:99], v[162:163]
	s_waitcnt vmcnt(0)
	s_cbranch_vccnz .LBB0_1086
	v_lshl_add_u64 v[162:163], v[144:145], 1, v[150:151]
	v_cvt_pk_bf16_f32 v158, v102, v103
	v_cvt_pk_bf16_f32 v159, v104, v105
	v_cvt_pk_bf16_f32 v160, v98, v99
	v_cvt_pk_bf16_f32 v161, v100, v101
	global_store_dwordx4 v[162:163], v[158:161], off
.LBB0_1086:
	s_and_b64 vcc, exec, s[6:7]
	v_lshlrev_b32_e32 v147, 16, v176
	v_lshlrev_b32_e32 v163, 16, v180
	v_and_b32_e32 v180, 0xffff0000, v180
	v_lshlrev_b32_e32 v164, 16, v181
	v_and_b32_e32 v181, 0xffff0000, v181
	v_lshlrev_b32_e32 v167, 16, v182
	v_and_b32_e32 v182, 0xffff0000, v182
	v_lshlrev_b32_e32 v168, 16, v183
	v_and_b32_e32 v183, 0xffff0000, v183
	v_max_f32_e32 v163, 0x1e3ce508, v163
	v_max_f32_e32 v180, 0x1e3ce508, v180
	v_max_f32_e32 v164, 0x1e3ce508, v164
	v_max_f32_e32 v181, 0x1e3ce508, v181
	v_max_f32_e32 v167, 0x1e3ce508, v167
	v_max_f32_e32 v182, 0x1e3ce508, v182
	v_max_f32_e32 v168, 0x1e3ce508, v168
	v_max_f32_e32 v183, 0x1e3ce508, v183
	v_rcp_f32_e32 v163, v163
	v_rcp_f32_e32 v180, v180
	v_rcp_f32_e32 v164, v164
	v_rcp_f32_e32 v181, v181
	v_rcp_f32_e32 v167, v167
	v_rcp_f32_e32 v182, v182
	v_rcp_f32_e32 v168, v168
	v_rcp_f32_e32 v183, v183
	v_and_b32_e32 v176, 0xffff0000, v176
	v_lshlrev_b32_e32 v162, 16, v177
	v_and_b32_e32 v177, 0xffff0000, v177
	v_lshlrev_b32_e32 v165, 16, v178
	v_and_b32_e32 v178, 0xffff0000, v178
	v_lshlrev_b32_e32 v166, 16, v179
	v_and_b32_e32 v179, 0xffff0000, v179
	v_mov_b32_e32 v169, v180
	v_mov_b32_e32 v170, v181
	v_mov_b32_e32 v171, v182
	v_mov_b32_e32 v172, v183
	v_mul_f32_e32 v180, v163, v147
	v_mul_f32_e32 v181, v169, v176
	v_mul_f32_e32 v182, v164, v162
	v_mul_f32_e32 v183, v170, v177
	v_mul_f32_e32 v176, v167, v165
	v_mul_f32_e32 v177, v171, v178
	v_mul_f32_e32 v178, v168, v166
	v_mul_f32_e32 v179, v172, v179
	v_pk_mul_f32 v[72:73], v[72:73], v[182:183]
	v_pk_mul_f32 v[70:71], v[70:71], v[180:181]
	v_pk_mul_f32 v[68:69], v[68:69], v[178:179]
	v_pk_mul_f32 v[66:67], v[66:67], v[176:177]
	s_cbranch_vccnz .LBB0_1088
	v_lshl_add_u64 v[150:151], v[144:145], 1, v[150:151]
	v_cvt_pk_bf16_f32 v180, v70, v71
	v_cvt_pk_bf16_f32 v181, v72, v73
	v_cvt_pk_bf16_f32 v182, v66, v67
	v_cvt_pk_bf16_f32 v183, v68, v69
	global_store_dwordx4 v[150:151], v[180:183], off offset:256
.LBB0_1088:
	v_or_b32_e32 v150, 32, v146
	s_nop 0
	v_mov_b64_e32 v[152:153], s[8:9]
	v_mad_i64_i32 v[152:153], s[38:39], v150, s85, v[152:153]
	v_lshl_add_u64 v[154:155], v[152:153], 0, s[88:89]
	v_lshl_add_u64 v[152:153], s[34:35], 1, v[154:155]
	v_lshl_add_u64 v[154:155], s[36:37], 1, v[154:155]
	v_lshl_add_u64 v[152:153], v[152:153], 0, v[148:149]
	v_lshl_add_u64 v[154:155], v[154:155], 0, v[148:149]
	global_load_dwordx4 v[158:161], v[152:153], off
	global_load_dwordx4 v[162:165], v[154:155], off
	global_load_dwordx4 v[176:179], v[152:153], off offset:256
	global_load_dwordx4 v[180:183], v[154:155], off offset:256
	v_ashrrev_i32_e32 v151, 31, v150
	v_lshlrev_b64 v[150:151], 11, v[150:151]
	s_and_b64 vcc, exec, s[6:7]
	v_lshl_add_u64 v[150:151], s[10:11], 0, v[150:151]
	s_waitcnt vmcnt(3)
	v_lshlrev_b32_e32 v147, 16, v158
	v_and_b32_e32 v166, 0xffff0000, v158
	v_lshlrev_b32_e32 v167, 16, v159
	v_and_b32_e32 v168, 0xffff0000, v159
	s_waitcnt vmcnt(2)
	v_lshlrev_b32_e32 v158, 16, v162
	v_and_b32_e32 v159, 0xffff0000, v162
	v_lshlrev_b32_e32 v162, 16, v163
	v_and_b32_e32 v163, 0xffff0000, v163
	v_lshlrev_b32_e32 v169, 16, v160
	v_and_b32_e32 v170, 0xffff0000, v160
	v_lshlrev_b32_e32 v171, 16, v161
	v_and_b32_e32 v172, 0xffff0000, v161
	v_lshlrev_b32_e32 v160, 16, v164
	v_and_b32_e32 v161, 0xffff0000, v164
	v_lshlrev_b32_e32 v164, 16, v165
	v_and_b32_e32 v165, 0xffff0000, v165
	v_max_f32_e32 v158, 0x1e3ce508, v158
	v_max_f32_e32 v159, 0x1e3ce508, v159
	v_max_f32_e32 v162, 0x1e3ce508, v162
	v_max_f32_e32 v163, 0x1e3ce508, v163
	v_max_f32_e32 v160, 0x1e3ce508, v160
	v_max_f32_e32 v161, 0x1e3ce508, v161
	v_max_f32_e32 v164, 0x1e3ce508, v164
	v_max_f32_e32 v165, 0x1e3ce508, v165
	v_rcp_f32_e32 v158, v158
	v_rcp_f32_e32 v159, v159
	v_rcp_f32_e32 v162, v162
	v_rcp_f32_e32 v163, v163
	v_rcp_f32_e32 v160, v160
	v_rcp_f32_e32 v161, v161
	v_rcp_f32_e32 v164, v164
	v_rcp_f32_e32 v165, v165
	v_mov_b32_e32 v173, v160
	v_mov_b32_e32 v174, v161
	v_mul_f32_e32 v158, v158, v147
	v_mul_f32_e32 v159, v159, v166
	v_mul_f32_e32 v160, v162, v167
	v_mul_f32_e32 v161, v163, v168
	v_mul_f32_e32 v162, v173, v169
	v_mul_f32_e32 v163, v174, v170
	v_mul_f32_e32 v164, v164, v171
	v_mul_f32_e32 v165, v165, v172
	v_pk_mul_f32 v[96:97], v[96:97], v[160:161]
	v_pk_mul_f32 v[94:95], v[94:95], v[158:159]
	v_pk_mul_f32 v[92:93], v[92:93], v[164:165]
	v_pk_mul_f32 v[90:91], v[90:91], v[162:163]
	s_waitcnt vmcnt(0)
	s_cbranch_vccnz .LBB0_1090
	v_lshl_add_u64 v[162:163], v[144:145], 1, v[150:151]
	v_cvt_pk_bf16_f32 v158, v94, v95
	v_cvt_pk_bf16_f32 v159, v96, v97
	v_cvt_pk_bf16_f32 v160, v90, v91
	v_cvt_pk_bf16_f32 v161, v92, v93
	global_store_dwordx4 v[162:163], v[158:161], off
.LBB0_1090:
	s_and_b64 vcc, exec, s[6:7]
	v_lshlrev_b32_e32 v147, 16, v176
	v_lshlrev_b32_e32 v163, 16, v180
	v_and_b32_e32 v180, 0xffff0000, v180
	v_lshlrev_b32_e32 v164, 16, v181
	v_and_b32_e32 v181, 0xffff0000, v181
	v_lshlrev_b32_e32 v167, 16, v182
	v_and_b32_e32 v182, 0xffff0000, v182
	v_lshlrev_b32_e32 v168, 16, v183
	v_and_b32_e32 v183, 0xffff0000, v183
	v_max_f32_e32 v163, 0x1e3ce508, v163
	v_max_f32_e32 v180, 0x1e3ce508, v180
	v_max_f32_e32 v164, 0x1e3ce508, v164
	v_max_f32_e32 v181, 0x1e3ce508, v181
	v_max_f32_e32 v167, 0x1e3ce508, v167
	v_max_f32_e32 v182, 0x1e3ce508, v182
	v_max_f32_e32 v168, 0x1e3ce508, v168
	v_max_f32_e32 v183, 0x1e3ce508, v183
	v_rcp_f32_e32 v163, v163
	v_rcp_f32_e32 v180, v180
	v_rcp_f32_e32 v164, v164
	v_rcp_f32_e32 v181, v181
	v_rcp_f32_e32 v167, v167
	v_rcp_f32_e32 v182, v182
	v_rcp_f32_e32 v168, v168
	v_rcp_f32_e32 v183, v183
	v_and_b32_e32 v176, 0xffff0000, v176
	v_lshlrev_b32_e32 v162, 16, v177
	v_and_b32_e32 v177, 0xffff0000, v177
	v_lshlrev_b32_e32 v165, 16, v178
	v_and_b32_e32 v178, 0xffff0000, v178
	v_lshlrev_b32_e32 v166, 16, v179
	v_and_b32_e32 v179, 0xffff0000, v179
	v_mov_b32_e32 v169, v180
	v_mov_b32_e32 v170, v181
	v_mov_b32_e32 v171, v182
	v_mov_b32_e32 v172, v183
	v_mul_f32_e32 v180, v163, v147
	v_mul_f32_e32 v181, v169, v176
	v_mul_f32_e32 v182, v164, v162
	v_mul_f32_e32 v183, v170, v177
	v_mul_f32_e32 v176, v167, v165
	v_mul_f32_e32 v177, v171, v178
	v_mul_f32_e32 v178, v168, v166
	v_mul_f32_e32 v179, v172, v179
	v_pk_mul_f32 v[64:65], v[64:65], v[182:183]
	v_pk_mul_f32 v[62:63], v[62:63], v[180:181]
	v_pk_mul_f32 v[60:61], v[60:61], v[178:179]
	v_pk_mul_f32 v[58:59], v[58:59], v[176:177]
	s_cbranch_vccnz .LBB0_1092
	v_lshl_add_u64 v[150:151], v[144:145], 1, v[150:151]
	v_cvt_pk_bf16_f32 v180, v62, v63
	v_cvt_pk_bf16_f32 v181, v64, v65
	v_cvt_pk_bf16_f32 v182, v58, v59
	v_cvt_pk_bf16_f32 v183, v60, v61
	global_store_dwordx4 v[150:151], v[180:183], off offset:256
.LBB0_1092:
	v_or_b32_e32 v150, 48, v146
	s_nop 0
	v_mov_b64_e32 v[152:153], s[8:9]
	v_mad_i64_i32 v[152:153], s[38:39], v150, s85, v[152:153]
	v_lshl_add_u64 v[154:155], v[152:153], 0, s[88:89]
	v_lshl_add_u64 v[152:153], s[34:35], 1, v[154:155]
	v_lshl_add_u64 v[154:155], s[36:37], 1, v[154:155]
	v_lshl_add_u64 v[152:153], v[152:153], 0, v[148:149]
	v_lshl_add_u64 v[154:155], v[154:155], 0, v[148:149]
	global_load_dwordx4 v[158:161], v[152:153], off
	global_load_dwordx4 v[162:165], v[154:155], off
	global_load_dwordx4 v[176:179], v[152:153], off offset:256
	global_load_dwordx4 v[180:183], v[154:155], off offset:256
	v_ashrrev_i32_e32 v151, 31, v150
	v_lshlrev_b64 v[150:151], 11, v[150:151]
	s_and_b64 vcc, exec, s[6:7]
	v_lshl_add_u64 v[150:151], s[10:11], 0, v[150:151]
	s_waitcnt vmcnt(3)
	v_lshlrev_b32_e32 v147, 16, v158
	v_and_b32_e32 v166, 0xffff0000, v158
	v_lshlrev_b32_e32 v167, 16, v159
	v_and_b32_e32 v168, 0xffff0000, v159
	s_waitcnt vmcnt(2)
	v_lshlrev_b32_e32 v158, 16, v162
	v_and_b32_e32 v159, 0xffff0000, v162
	v_lshlrev_b32_e32 v162, 16, v163
	v_and_b32_e32 v163, 0xffff0000, v163
	v_lshlrev_b32_e32 v169, 16, v160
	v_and_b32_e32 v170, 0xffff0000, v160
	v_lshlrev_b32_e32 v171, 16, v161
	v_and_b32_e32 v172, 0xffff0000, v161
	v_lshlrev_b32_e32 v160, 16, v164
	v_and_b32_e32 v161, 0xffff0000, v164
	v_lshlrev_b32_e32 v164, 16, v165
	v_and_b32_e32 v165, 0xffff0000, v165
	v_max_f32_e32 v158, 0x1e3ce508, v158
	v_max_f32_e32 v159, 0x1e3ce508, v159
	v_max_f32_e32 v162, 0x1e3ce508, v162
	v_max_f32_e32 v163, 0x1e3ce508, v163
	v_max_f32_e32 v160, 0x1e3ce508, v160
	v_max_f32_e32 v161, 0x1e3ce508, v161
	v_max_f32_e32 v164, 0x1e3ce508, v164
	v_max_f32_e32 v165, 0x1e3ce508, v165
	v_rcp_f32_e32 v158, v158
	v_rcp_f32_e32 v159, v159
	v_rcp_f32_e32 v162, v162
	v_rcp_f32_e32 v163, v163
	v_rcp_f32_e32 v160, v160
	v_rcp_f32_e32 v161, v161
	v_rcp_f32_e32 v164, v164
	v_rcp_f32_e32 v165, v165
	v_mov_b32_e32 v173, v160
	v_mov_b32_e32 v174, v161
	v_mul_f32_e32 v158, v158, v147
	v_mul_f32_e32 v159, v159, v166
	v_mul_f32_e32 v160, v162, v167
	v_mul_f32_e32 v161, v163, v168
	v_mul_f32_e32 v162, v173, v169
	v_mul_f32_e32 v163, v174, v170
	v_mul_f32_e32 v164, v164, v171
	v_mul_f32_e32 v165, v165, v172
	v_pk_mul_f32 v[88:89], v[88:89], v[160:161]
	v_pk_mul_f32 v[86:87], v[86:87], v[158:159]
	v_pk_mul_f32 v[84:85], v[84:85], v[164:165]
	v_pk_mul_f32 v[82:83], v[82:83], v[162:163]
	s_waitcnt vmcnt(0)
	s_cbranch_vccnz .LBB0_1094
	v_lshl_add_u64 v[162:163], v[144:145], 1, v[150:151]
	v_cvt_pk_bf16_f32 v158, v86, v87
	v_cvt_pk_bf16_f32 v159, v88, v89
	v_cvt_pk_bf16_f32 v160, v82, v83
	v_cvt_pk_bf16_f32 v161, v84, v85
	global_store_dwordx4 v[162:163], v[158:161], off
.LBB0_1094:
	s_and_b64 vcc, exec, s[6:7]
	v_lshlrev_b32_e32 v147, 16, v176
	v_lshlrev_b32_e32 v163, 16, v180
	v_and_b32_e32 v180, 0xffff0000, v180
	v_lshlrev_b32_e32 v164, 16, v181
	v_and_b32_e32 v181, 0xffff0000, v181
	v_lshlrev_b32_e32 v167, 16, v182
	v_and_b32_e32 v182, 0xffff0000, v182
	v_lshlrev_b32_e32 v168, 16, v183
	v_and_b32_e32 v183, 0xffff0000, v183
	v_max_f32_e32 v163, 0x1e3ce508, v163
	v_max_f32_e32 v180, 0x1e3ce508, v180
	v_max_f32_e32 v164, 0x1e3ce508, v164
	v_max_f32_e32 v181, 0x1e3ce508, v181
	v_max_f32_e32 v167, 0x1e3ce508, v167
	v_max_f32_e32 v182, 0x1e3ce508, v182
	v_max_f32_e32 v168, 0x1e3ce508, v168
	v_max_f32_e32 v183, 0x1e3ce508, v183
	v_rcp_f32_e32 v163, v163
	v_rcp_f32_e32 v180, v180
	v_rcp_f32_e32 v164, v164
	v_rcp_f32_e32 v181, v181
	v_rcp_f32_e32 v167, v167
	v_rcp_f32_e32 v182, v182
	v_rcp_f32_e32 v168, v168
	v_rcp_f32_e32 v183, v183
	v_and_b32_e32 v176, 0xffff0000, v176
	v_lshlrev_b32_e32 v162, 16, v177
	v_and_b32_e32 v177, 0xffff0000, v177
	v_lshlrev_b32_e32 v165, 16, v178
	v_and_b32_e32 v178, 0xffff0000, v178
	v_lshlrev_b32_e32 v166, 16, v179
	v_and_b32_e32 v179, 0xffff0000, v179
	v_mov_b32_e32 v169, v180
	v_mov_b32_e32 v170, v181
	v_mov_b32_e32 v171, v182
	v_mov_b32_e32 v172, v183
	v_mul_f32_e32 v180, v163, v147
	v_mul_f32_e32 v181, v169, v176
	v_mul_f32_e32 v182, v164, v162
	v_mul_f32_e32 v183, v170, v177
	v_mul_f32_e32 v176, v167, v165
	v_mul_f32_e32 v177, v171, v178
	v_mul_f32_e32 v178, v168, v166
	v_mul_f32_e32 v179, v172, v179
	v_pk_mul_f32 v[56:57], v[56:57], v[182:183]
	v_pk_mul_f32 v[54:55], v[54:55], v[180:181]
	v_pk_mul_f32 v[52:53], v[52:53], v[178:179]
	v_pk_mul_f32 v[50:51], v[50:51], v[176:177]
	s_cbranch_vccnz .LBB0_1096
	v_lshl_add_u64 v[150:151], v[144:145], 1, v[150:151]
	v_cvt_pk_bf16_f32 v180, v54, v55
	v_cvt_pk_bf16_f32 v181, v56, v57
	v_cvt_pk_bf16_f32 v182, v50, v51
	v_cvt_pk_bf16_f32 v183, v52, v53
	global_store_dwordx4 v[150:151], v[180:183], off offset:256
.LBB0_1096:
	v_add_u32_e32 v150, 0x80, v146
	s_nop 0
	v_mov_b64_e32 v[152:153], s[8:9]
	v_mad_i64_i32 v[152:153], s[38:39], v150, s85, v[152:153]
	v_lshl_add_u64 v[154:155], v[152:153], 0, s[88:89]
	v_lshl_add_u64 v[152:153], s[34:35], 1, v[154:155]
	v_lshl_add_u64 v[154:155], s[36:37], 1, v[154:155]
	v_lshl_add_u64 v[152:153], v[152:153], 0, v[148:149]
	v_lshl_add_u64 v[154:155], v[154:155], 0, v[148:149]
	global_load_dwordx4 v[158:161], v[152:153], off
	global_load_dwordx4 v[162:165], v[154:155], off
	global_load_dwordx4 v[176:179], v[152:153], off offset:256
	global_load_dwordx4 v[180:183], v[154:155], off offset:256
	v_ashrrev_i32_e32 v151, 31, v150
	v_lshlrev_b64 v[150:151], 11, v[150:151]
	s_and_b64 vcc, exec, s[6:7]
	v_lshl_add_u64 v[150:151], s[10:11], 0, v[150:151]
	s_waitcnt vmcnt(3)
	v_lshlrev_b32_e32 v147, 16, v158
	v_and_b32_e32 v166, 0xffff0000, v158
	v_lshlrev_b32_e32 v167, 16, v159
	v_and_b32_e32 v168, 0xffff0000, v159
	s_waitcnt vmcnt(2)
	v_lshlrev_b32_e32 v158, 16, v162
	v_and_b32_e32 v159, 0xffff0000, v162
	v_lshlrev_b32_e32 v162, 16, v163
	v_and_b32_e32 v163, 0xffff0000, v163
	v_lshlrev_b32_e32 v169, 16, v160
	v_and_b32_e32 v170, 0xffff0000, v160
	v_lshlrev_b32_e32 v171, 16, v161
	v_and_b32_e32 v172, 0xffff0000, v161
	v_lshlrev_b32_e32 v160, 16, v164
	v_and_b32_e32 v161, 0xffff0000, v164
	v_lshlrev_b32_e32 v164, 16, v165
	v_and_b32_e32 v165, 0xffff0000, v165
	v_max_f32_e32 v158, 0x1e3ce508, v158
	v_max_f32_e32 v159, 0x1e3ce508, v159
	v_max_f32_e32 v162, 0x1e3ce508, v162
	v_max_f32_e32 v163, 0x1e3ce508, v163
	v_max_f32_e32 v160, 0x1e3ce508, v160
	v_max_f32_e32 v161, 0x1e3ce508, v161
	v_max_f32_e32 v164, 0x1e3ce508, v164
	v_max_f32_e32 v165, 0x1e3ce508, v165
	v_rcp_f32_e32 v158, v158
	v_rcp_f32_e32 v159, v159
	v_rcp_f32_e32 v162, v162
	v_rcp_f32_e32 v163, v163
	v_rcp_f32_e32 v160, v160
	v_rcp_f32_e32 v161, v161
	v_rcp_f32_e32 v164, v164
	v_rcp_f32_e32 v165, v165
	v_mov_b32_e32 v173, v160
	v_mov_b32_e32 v174, v161
	v_mul_f32_e32 v158, v158, v147
	v_mul_f32_e32 v159, v159, v166
	v_mul_f32_e32 v160, v162, v167
	v_mul_f32_e32 v161, v163, v168
	v_mul_f32_e32 v162, v173, v169
	v_mul_f32_e32 v163, v174, v170
	v_mul_f32_e32 v164, v164, v171
	v_mul_f32_e32 v165, v165, v172
	v_pk_mul_f32 v[48:49], v[48:49], v[160:161]
	v_pk_mul_f32 v[46:47], v[46:47], v[158:159]
	v_pk_mul_f32 v[44:45], v[44:45], v[164:165]
	v_pk_mul_f32 v[42:43], v[42:43], v[162:163]
	s_waitcnt vmcnt(0)
	s_cbranch_vccnz .LBB0_1098
	v_lshl_add_u64 v[162:163], v[144:145], 1, v[150:151]
	v_cvt_pk_bf16_f32 v158, v46, v47
	v_cvt_pk_bf16_f32 v159, v48, v49
	v_cvt_pk_bf16_f32 v160, v42, v43
	v_cvt_pk_bf16_f32 v161, v44, v45
	global_store_dwordx4 v[162:163], v[158:161], off
.LBB0_1098:
	s_and_b64 vcc, exec, s[6:7]
	v_lshlrev_b32_e32 v147, 16, v176
	v_lshlrev_b32_e32 v163, 16, v180
	v_and_b32_e32 v180, 0xffff0000, v180
	v_lshlrev_b32_e32 v164, 16, v181
	v_and_b32_e32 v181, 0xffff0000, v181
	v_lshlrev_b32_e32 v167, 16, v182
	v_and_b32_e32 v182, 0xffff0000, v182
	v_lshlrev_b32_e32 v168, 16, v183
	v_and_b32_e32 v183, 0xffff0000, v183
	v_max_f32_e32 v163, 0x1e3ce508, v163
	v_max_f32_e32 v180, 0x1e3ce508, v180
	v_max_f32_e32 v164, 0x1e3ce508, v164
	v_max_f32_e32 v181, 0x1e3ce508, v181
	v_max_f32_e32 v167, 0x1e3ce508, v167
	v_max_f32_e32 v182, 0x1e3ce508, v182
	v_max_f32_e32 v168, 0x1e3ce508, v168
	v_max_f32_e32 v183, 0x1e3ce508, v183
	v_rcp_f32_e32 v163, v163
	v_rcp_f32_e32 v180, v180
	v_rcp_f32_e32 v164, v164
	v_rcp_f32_e32 v181, v181
	v_rcp_f32_e32 v167, v167
	v_rcp_f32_e32 v182, v182
	v_rcp_f32_e32 v168, v168
	v_rcp_f32_e32 v183, v183
	v_and_b32_e32 v176, 0xffff0000, v176
	v_lshlrev_b32_e32 v162, 16, v177
	v_and_b32_e32 v177, 0xffff0000, v177
	v_lshlrev_b32_e32 v165, 16, v178
	v_and_b32_e32 v178, 0xffff0000, v178
	v_lshlrev_b32_e32 v166, 16, v179
	v_and_b32_e32 v179, 0xffff0000, v179
	v_mov_b32_e32 v169, v180
	v_mov_b32_e32 v170, v181
	v_mov_b32_e32 v171, v182
	v_mov_b32_e32 v172, v183
	v_mul_f32_e32 v180, v163, v147
	v_mul_f32_e32 v181, v169, v176
	v_mul_f32_e32 v182, v164, v162
	v_mul_f32_e32 v183, v170, v177
	v_mul_f32_e32 v176, v167, v165
	v_mul_f32_e32 v177, v171, v178
	v_mul_f32_e32 v178, v168, v166
	v_mul_f32_e32 v179, v172, v179
	v_pk_mul_f32 v[16:17], v[16:17], v[182:183]
	v_pk_mul_f32 v[14:15], v[14:15], v[180:181]
	v_pk_mul_f32 v[12:13], v[12:13], v[178:179]
	v_pk_mul_f32 v[10:11], v[10:11], v[176:177]
	s_cbranch_vccnz .LBB0_1100
	v_lshl_add_u64 v[150:151], v[144:145], 1, v[150:151]
	v_cvt_pk_bf16_f32 v180, v14, v15
	v_cvt_pk_bf16_f32 v181, v16, v17
	v_cvt_pk_bf16_f32 v182, v10, v11
	v_cvt_pk_bf16_f32 v183, v12, v13
	global_store_dwordx4 v[150:151], v[180:183], off offset:256
.LBB0_1100:
	v_add_u32_e32 v150, 0x90, v146
	s_nop 0
	v_mov_b64_e32 v[152:153], s[8:9]
	v_mad_i64_i32 v[152:153], s[38:39], v150, s85, v[152:153]
	v_lshl_add_u64 v[154:155], v[152:153], 0, s[88:89]
	v_lshl_add_u64 v[152:153], s[34:35], 1, v[154:155]
	v_lshl_add_u64 v[154:155], s[36:37], 1, v[154:155]
	v_lshl_add_u64 v[152:153], v[152:153], 0, v[148:149]
	v_lshl_add_u64 v[154:155], v[154:155], 0, v[148:149]
	global_load_dwordx4 v[158:161], v[152:153], off
	global_load_dwordx4 v[162:165], v[154:155], off
	global_load_dwordx4 v[176:179], v[152:153], off offset:256
	global_load_dwordx4 v[180:183], v[154:155], off offset:256
	v_ashrrev_i32_e32 v151, 31, v150
	v_lshlrev_b64 v[150:151], 11, v[150:151]
	s_and_b64 vcc, exec, s[6:7]
	v_lshl_add_u64 v[150:151], s[10:11], 0, v[150:151]
	s_waitcnt vmcnt(3)
	v_lshlrev_b32_e32 v147, 16, v158
	v_and_b32_e32 v166, 0xffff0000, v158
	v_lshlrev_b32_e32 v167, 16, v159
	v_and_b32_e32 v168, 0xffff0000, v159
	s_waitcnt vmcnt(2)
	v_lshlrev_b32_e32 v158, 16, v162
	v_and_b32_e32 v159, 0xffff0000, v162
	v_lshlrev_b32_e32 v162, 16, v163
	v_and_b32_e32 v163, 0xffff0000, v163
	v_lshlrev_b32_e32 v169, 16, v160
	v_and_b32_e32 v170, 0xffff0000, v160
	v_lshlrev_b32_e32 v171, 16, v161
	v_and_b32_e32 v172, 0xffff0000, v161
	v_lshlrev_b32_e32 v160, 16, v164
	v_and_b32_e32 v161, 0xffff0000, v164
	v_lshlrev_b32_e32 v164, 16, v165
	v_and_b32_e32 v165, 0xffff0000, v165
	v_max_f32_e32 v158, 0x1e3ce508, v158
	v_max_f32_e32 v159, 0x1e3ce508, v159
	v_max_f32_e32 v162, 0x1e3ce508, v162
	v_max_f32_e32 v163, 0x1e3ce508, v163
	v_max_f32_e32 v160, 0x1e3ce508, v160
	v_max_f32_e32 v161, 0x1e3ce508, v161
	v_max_f32_e32 v164, 0x1e3ce508, v164
	v_max_f32_e32 v165, 0x1e3ce508, v165
	v_rcp_f32_e32 v158, v158
	v_rcp_f32_e32 v159, v159
	v_rcp_f32_e32 v162, v162
	v_rcp_f32_e32 v163, v163
	v_rcp_f32_e32 v160, v160
	v_rcp_f32_e32 v161, v161
	v_rcp_f32_e32 v164, v164
	v_rcp_f32_e32 v165, v165
	v_mov_b32_e32 v173, v160
	v_mov_b32_e32 v174, v161
	v_mul_f32_e32 v158, v158, v147
	v_mul_f32_e32 v159, v159, v166
	v_mul_f32_e32 v160, v162, v167
	v_mul_f32_e32 v161, v163, v168
	v_mul_f32_e32 v162, v173, v169
	v_mul_f32_e32 v163, v174, v170
	v_mul_f32_e32 v164, v164, v171
	v_mul_f32_e32 v165, v165, v172
	v_pk_mul_f32 v[40:41], v[40:41], v[160:161]
	v_pk_mul_f32 v[38:39], v[38:39], v[158:159]
	v_pk_mul_f32 v[36:37], v[36:37], v[164:165]
	v_pk_mul_f32 v[34:35], v[34:35], v[162:163]
	s_waitcnt vmcnt(0)
	s_cbranch_vccnz .LBB0_1102
	v_lshl_add_u64 v[162:163], v[144:145], 1, v[150:151]
	v_cvt_pk_bf16_f32 v158, v38, v39
	v_cvt_pk_bf16_f32 v159, v40, v41
	v_cvt_pk_bf16_f32 v160, v34, v35
	v_cvt_pk_bf16_f32 v161, v36, v37
	global_store_dwordx4 v[162:163], v[158:161], off
.LBB0_1102:
	s_and_b64 vcc, exec, s[6:7]
	v_lshlrev_b32_e32 v147, 16, v176
	v_lshlrev_b32_e32 v163, 16, v180
	v_and_b32_e32 v180, 0xffff0000, v180
	v_lshlrev_b32_e32 v164, 16, v181
	v_and_b32_e32 v181, 0xffff0000, v181
	v_lshlrev_b32_e32 v167, 16, v182
	v_and_b32_e32 v182, 0xffff0000, v182
	v_lshlrev_b32_e32 v168, 16, v183
	v_and_b32_e32 v183, 0xffff0000, v183
	v_max_f32_e32 v163, 0x1e3ce508, v163
	v_max_f32_e32 v180, 0x1e3ce508, v180
	v_max_f32_e32 v164, 0x1e3ce508, v164
	v_max_f32_e32 v181, 0x1e3ce508, v181
	v_max_f32_e32 v167, 0x1e3ce508, v167
	v_max_f32_e32 v182, 0x1e3ce508, v182
	v_max_f32_e32 v168, 0x1e3ce508, v168
	v_max_f32_e32 v183, 0x1e3ce508, v183
	v_rcp_f32_e32 v163, v163
	v_rcp_f32_e32 v180, v180
	v_rcp_f32_e32 v164, v164
	v_rcp_f32_e32 v181, v181
	v_rcp_f32_e32 v167, v167
	v_rcp_f32_e32 v182, v182
	v_rcp_f32_e32 v168, v168
	v_rcp_f32_e32 v183, v183
	v_and_b32_e32 v176, 0xffff0000, v176
	v_lshlrev_b32_e32 v162, 16, v177
	v_and_b32_e32 v177, 0xffff0000, v177
	v_lshlrev_b32_e32 v165, 16, v178
	v_and_b32_e32 v178, 0xffff0000, v178
	v_lshlrev_b32_e32 v166, 16, v179
	v_and_b32_e32 v179, 0xffff0000, v179
	v_mov_b32_e32 v169, v180
	v_mov_b32_e32 v170, v181
	v_mov_b32_e32 v171, v182
	v_mov_b32_e32 v172, v183
	v_mul_f32_e32 v180, v163, v147
	v_mul_f32_e32 v181, v169, v176
	v_mul_f32_e32 v182, v164, v162
	v_mul_f32_e32 v183, v170, v177
	v_mul_f32_e32 v176, v167, v165
	v_mul_f32_e32 v177, v171, v178
	v_mul_f32_e32 v178, v168, v166
	v_mul_f32_e32 v179, v172, v179
	v_pk_mul_f32 v[8:9], v[8:9], v[182:183]
	v_pk_mul_f32 v[6:7], v[6:7], v[180:181]
	v_pk_mul_f32 v[4:5], v[4:5], v[178:179]
	v_pk_mul_f32 v[2:3], v[2:3], v[176:177]
	s_cbranch_vccnz .LBB0_1104
	v_lshl_add_u64 v[150:151], v[144:145], 1, v[150:151]
	v_cvt_pk_bf16_f32 v180, v6, v7
	v_cvt_pk_bf16_f32 v181, v8, v9
	v_cvt_pk_bf16_f32 v182, v2, v3
	v_cvt_pk_bf16_f32 v183, v4, v5
	global_store_dwordx4 v[150:151], v[180:183], off offset:256
.LBB0_1104:
	v_add_u32_e32 v150, 0xa0, v146
	s_nop 0
	v_mov_b64_e32 v[152:153], s[8:9]
	v_mad_i64_i32 v[152:153], s[38:39], v150, s85, v[152:153]
	v_lshl_add_u64 v[154:155], v[152:153], 0, s[88:89]
	v_lshl_add_u64 v[152:153], s[34:35], 1, v[154:155]
	v_lshl_add_u64 v[154:155], s[36:37], 1, v[154:155]
	v_lshl_add_u64 v[152:153], v[152:153], 0, v[148:149]
	v_lshl_add_u64 v[154:155], v[154:155], 0, v[148:149]
	global_load_dwordx4 v[158:161], v[152:153], off
	global_load_dwordx4 v[162:165], v[154:155], off
	global_load_dwordx4 v[176:179], v[152:153], off offset:256
	global_load_dwordx4 v[180:183], v[154:155], off offset:256
	v_ashrrev_i32_e32 v151, 31, v150
	v_lshlrev_b64 v[150:151], 11, v[150:151]
	s_and_b64 vcc, exec, s[6:7]
	v_lshl_add_u64 v[150:151], s[10:11], 0, v[150:151]
	s_waitcnt vmcnt(3)
	v_lshlrev_b32_e32 v147, 16, v158
	v_and_b32_e32 v166, 0xffff0000, v158
	v_lshlrev_b32_e32 v167, 16, v159
	v_and_b32_e32 v168, 0xffff0000, v159
	s_waitcnt vmcnt(2)
	v_lshlrev_b32_e32 v158, 16, v162
	v_and_b32_e32 v159, 0xffff0000, v162
	v_lshlrev_b32_e32 v162, 16, v163
	v_and_b32_e32 v163, 0xffff0000, v163
	v_lshlrev_b32_e32 v169, 16, v160
	v_and_b32_e32 v170, 0xffff0000, v160
	v_lshlrev_b32_e32 v171, 16, v161
	v_and_b32_e32 v172, 0xffff0000, v161
	v_lshlrev_b32_e32 v160, 16, v164
	v_and_b32_e32 v161, 0xffff0000, v164
	v_lshlrev_b32_e32 v164, 16, v165
	v_and_b32_e32 v165, 0xffff0000, v165
	v_max_f32_e32 v158, 0x1e3ce508, v158
	v_max_f32_e32 v159, 0x1e3ce508, v159
	v_max_f32_e32 v162, 0x1e3ce508, v162
	v_max_f32_e32 v163, 0x1e3ce508, v163
	v_max_f32_e32 v160, 0x1e3ce508, v160
	v_max_f32_e32 v161, 0x1e3ce508, v161
	v_max_f32_e32 v164, 0x1e3ce508, v164
	v_max_f32_e32 v165, 0x1e3ce508, v165
	v_rcp_f32_e32 v158, v158
	v_rcp_f32_e32 v159, v159
	v_rcp_f32_e32 v162, v162
	v_rcp_f32_e32 v163, v163
	v_rcp_f32_e32 v160, v160
	v_rcp_f32_e32 v161, v161
	v_rcp_f32_e32 v164, v164
	v_rcp_f32_e32 v165, v165
	v_mov_b32_e32 v173, v160
	v_mov_b32_e32 v174, v161
	v_mul_f32_e32 v158, v158, v147
	v_mul_f32_e32 v159, v159, v166
	v_mul_f32_e32 v160, v162, v167
	v_mul_f32_e32 v161, v163, v168
	v_mul_f32_e32 v162, v173, v169
	v_mul_f32_e32 v163, v174, v170
	v_mul_f32_e32 v164, v164, v171
	v_mul_f32_e32 v165, v165, v172
	v_pk_mul_f32 v[32:33], v[32:33], v[160:161]
	v_pk_mul_f32 v[30:31], v[30:31], v[158:159]
	v_pk_mul_f32 v[28:29], v[28:29], v[164:165]
	v_pk_mul_f32 v[26:27], v[26:27], v[162:163]
	s_waitcnt vmcnt(0)
	s_cbranch_vccnz .LBB0_1106
	v_lshl_add_u64 v[162:163], v[144:145], 1, v[150:151]
	v_cvt_pk_bf16_f32 v158, v30, v31
	v_cvt_pk_bf16_f32 v159, v32, v33
	v_cvt_pk_bf16_f32 v160, v26, v27
	v_cvt_pk_bf16_f32 v161, v28, v29
	global_store_dwordx4 v[162:163], v[158:161], off
.LBB0_1106:
	s_and_b64 vcc, exec, s[6:7]
	v_lshlrev_b32_e32 v147, 16, v176
	v_lshlrev_b32_e32 v163, 16, v180
	v_and_b32_e32 v180, 0xffff0000, v180
	v_lshlrev_b32_e32 v164, 16, v181
	v_and_b32_e32 v181, 0xffff0000, v181
	v_lshlrev_b32_e32 v167, 16, v182
	v_and_b32_e32 v182, 0xffff0000, v182
	v_lshlrev_b32_e32 v168, 16, v183
	v_and_b32_e32 v183, 0xffff0000, v183
	v_max_f32_e32 v163, 0x1e3ce508, v163
	v_max_f32_e32 v180, 0x1e3ce508, v180
	v_max_f32_e32 v164, 0x1e3ce508, v164
	v_max_f32_e32 v181, 0x1e3ce508, v181
	v_max_f32_e32 v167, 0x1e3ce508, v167
	v_max_f32_e32 v182, 0x1e3ce508, v182
	v_max_f32_e32 v168, 0x1e3ce508, v168
	v_max_f32_e32 v183, 0x1e3ce508, v183
	v_rcp_f32_e32 v163, v163
	v_rcp_f32_e32 v180, v180
	v_rcp_f32_e32 v164, v164
	v_rcp_f32_e32 v181, v181
	v_rcp_f32_e32 v167, v167
	v_rcp_f32_e32 v182, v182
	v_rcp_f32_e32 v168, v168
	v_rcp_f32_e32 v183, v183
	v_and_b32_e32 v176, 0xffff0000, v176
	v_lshlrev_b32_e32 v162, 16, v177
	v_and_b32_e32 v177, 0xffff0000, v177
	v_lshlrev_b32_e32 v165, 16, v178
	v_and_b32_e32 v178, 0xffff0000, v178
	v_lshlrev_b32_e32 v166, 16, v179
	v_and_b32_e32 v179, 0xffff0000, v179
	v_mov_b32_e32 v169, v180
	v_mov_b32_e32 v170, v181
	v_mov_b32_e32 v171, v182
	v_mov_b32_e32 v172, v183
	v_mul_f32_e32 v180, v163, v147
	v_mul_f32_e32 v181, v169, v176
	v_mul_f32_e32 v182, v164, v162
	v_mul_f32_e32 v183, v170, v177
	v_mul_f32_e32 v176, v167, v165
	v_mul_f32_e32 v177, v171, v178
	v_mul_f32_e32 v178, v168, v166
	v_mul_f32_e32 v179, v172, v179
	v_pk_mul_f32 v[116:117], v[116:117], v[182:183]
	v_pk_mul_f32 v[114:115], v[114:115], v[180:181]
	v_pk_mul_f32 v[120:121], v[120:121], v[178:179]
	v_pk_mul_f32 v[118:119], v[118:119], v[176:177]
	s_cbranch_vccnz .LBB0_1108
	v_lshl_add_u64 v[150:151], v[144:145], 1, v[150:151]
	v_cvt_pk_bf16_f32 v180, v114, v115
	v_cvt_pk_bf16_f32 v181, v116, v117
	v_cvt_pk_bf16_f32 v182, v118, v119
	v_cvt_pk_bf16_f32 v183, v120, v121
	global_store_dwordx4 v[150:151], v[180:183], off offset:256
.LBB0_1108:
	v_add_u32_e32 v146, 0xb0, v146
	v_mov_b64_e32 v[150:151], s[8:9]
	v_mad_i64_i32 v[150:151], s[38:39], v146, s85, v[150:151]
	v_lshl_add_u64 v[158:159], v[150:151], 0, s[88:89]
	v_lshl_add_u64 v[150:151], s[34:35], 1, v[158:159]
	v_lshl_add_u64 v[158:159], s[36:37], 1, v[158:159]
	v_lshl_add_u64 v[150:151], v[150:151], 0, v[148:149]
	v_lshl_add_u64 v[148:149], v[158:159], 0, v[148:149]
	global_load_dwordx4 v[152:155], v[150:151], off
	global_load_dwordx4 v[158:161], v[148:149], off
	v_ashrrev_i32_e32 v147, 31, v146
	v_lshlrev_b64 v[146:147], 11, v[146:147]
	s_and_b64 vcc, exec, s[6:7]
	v_lshl_add_u64 v[146:147], s[10:11], 0, v[146:147]
	s_waitcnt vmcnt(1)
	v_lshlrev_b32_e32 v162, 16, v152
	v_and_b32_e32 v163, 0xffff0000, v152
	v_lshlrev_b32_e32 v164, 16, v153
	v_and_b32_e32 v165, 0xffff0000, v153
	s_waitcnt vmcnt(0)
	v_lshlrev_b32_e32 v152, 16, v158
	v_and_b32_e32 v153, 0xffff0000, v158
	v_lshlrev_b32_e32 v158, 16, v159
	v_and_b32_e32 v159, 0xffff0000, v159
	v_lshlrev_b32_e32 v166, 16, v154
	v_and_b32_e32 v167, 0xffff0000, v154
	v_lshlrev_b32_e32 v168, 16, v155
	v_and_b32_e32 v169, 0xffff0000, v155
	v_lshlrev_b32_e32 v154, 16, v160
	v_and_b32_e32 v155, 0xffff0000, v160
	v_lshlrev_b32_e32 v160, 16, v161
	v_and_b32_e32 v161, 0xffff0000, v161
	v_max_f32_e32 v152, 0x1e3ce508, v152
	v_max_f32_e32 v153, 0x1e3ce508, v153
	v_max_f32_e32 v158, 0x1e3ce508, v158
	v_max_f32_e32 v159, 0x1e3ce508, v159
	v_max_f32_e32 v154, 0x1e3ce508, v154
	v_max_f32_e32 v155, 0x1e3ce508, v155
	v_max_f32_e32 v160, 0x1e3ce508, v160
	v_max_f32_e32 v161, 0x1e3ce508, v161
	v_rcp_f32_e32 v152, v152
	v_rcp_f32_e32 v153, v153
	v_rcp_f32_e32 v158, v158
	v_rcp_f32_e32 v159, v159
	v_rcp_f32_e32 v154, v154
	v_rcp_f32_e32 v155, v155
	v_rcp_f32_e32 v160, v160
	v_rcp_f32_e32 v161, v161
	v_mov_b32_e32 v170, v154
	v_mov_b32_e32 v171, v155
	v_mul_f32_e32 v152, v152, v162
	v_mul_f32_e32 v153, v153, v163
	v_mul_f32_e32 v154, v158, v164
	v_mul_f32_e32 v155, v159, v165
	v_mul_f32_e32 v158, v170, v166
	v_mul_f32_e32 v159, v171, v167
	v_mul_f32_e32 v160, v160, v168
	v_mul_f32_e32 v161, v161, v169
	v_pk_mul_f32 v[24:25], v[24:25], v[154:155]
	v_pk_mul_f32 v[22:23], v[22:23], v[152:153]
	v_pk_mul_f32 v[20:21], v[20:21], v[160:161]
	v_pk_mul_f32 v[18:19], v[18:19], v[158:159]
	s_cbranch_vccnz .LBB0_1110
	v_lshl_add_u64 v[158:159], v[144:145], 1, v[146:147]
	v_cvt_pk_bf16_f32 v152, v22, v23
	v_cvt_pk_bf16_f32 v153, v24, v25
	v_cvt_pk_bf16_f32 v154, v18, v19
	v_cvt_pk_bf16_f32 v155, v20, v21
	global_store_dwordx4 v[158:159], v[152:155], off
.LBB0_1110:
	global_load_dwordx4 v[150:153], v[150:151], off offset:256
	s_nop 0
	global_load_dwordx4 v[158:161], v[148:149], off offset:256
	s_and_b64 vcc, exec, s[6:7]
	s_waitcnt vmcnt(1)
	v_lshlrev_b32_e32 v162, 16, v152
	s_waitcnt vmcnt(0)
	v_lshlrev_b32_e32 v154, 16, v158
	v_and_b32_e32 v155, 0xffff0000, v158
	v_lshlrev_b32_e32 v158, 16, v159
	v_and_b32_e32 v159, 0xffff0000, v159
	v_and_b32_e32 v163, 0xffff0000, v152
	v_lshlrev_b32_e32 v164, 16, v153
	v_and_b32_e32 v165, 0xffff0000, v153
	v_lshlrev_b32_e32 v152, 16, v160
	v_and_b32_e32 v153, 0xffff0000, v160
	v_lshlrev_b32_e32 v160, 16, v161
	v_and_b32_e32 v161, 0xffff0000, v161
	v_max_f32_e32 v154, 0x1e3ce508, v154
	v_max_f32_e32 v155, 0x1e3ce508, v155
	v_max_f32_e32 v158, 0x1e3ce508, v158
	v_max_f32_e32 v159, 0x1e3ce508, v159
	v_max_f32_e32 v152, 0x1e3ce508, v152
	v_max_f32_e32 v153, 0x1e3ce508, v153
	v_max_f32_e32 v160, 0x1e3ce508, v160
	v_max_f32_e32 v161, 0x1e3ce508, v161
	v_rcp_f32_e32 v154, v154
	v_rcp_f32_e32 v155, v155
	v_rcp_f32_e32 v158, v158
	v_rcp_f32_e32 v159, v159
	v_rcp_f32_e32 v152, v152
	v_rcp_f32_e32 v153, v153
	v_rcp_f32_e32 v160, v160
	v_rcp_f32_e32 v161, v161
	v_lshlrev_b32_e32 v148, 16, v150
	v_and_b32_e32 v149, 0xffff0000, v150
	v_lshlrev_b32_e32 v150, 16, v151
	v_and_b32_e32 v151, 0xffff0000, v151
	v_mul_f32_e32 v148, v154, v148
	v_mul_f32_e32 v149, v155, v149
	v_mul_f32_e32 v150, v158, v150
	v_mul_f32_e32 v151, v159, v151
	v_mul_f32_e32 v152, v152, v162
	v_mul_f32_e32 v153, v153, v163
	v_mul_f32_e32 v154, v160, v164
	v_mul_f32_e32 v155, v161, v165
	v_pk_mul_f32 v[124:125], v[124:125], v[150:151]
	v_pk_mul_f32 v[122:123], v[122:123], v[148:149]
	v_pk_mul_f32 v[128:129], v[128:129], v[154:155]
	v_pk_mul_f32 v[126:127], v[126:127], v[152:153]
	s_cbranch_vccnz .LBB0_1112
	v_lshl_add_u64 v[144:145], v[144:145], 1, v[146:147]
	v_cvt_pk_bf16_f32 v148, v122, v123
	v_cvt_pk_bf16_f32 v149, v124, v125
	v_cvt_pk_bf16_f32 v150, v126, v127
	v_cvt_pk_bf16_f32 v151, v128, v129
	global_store_dwordx4 v[144:145], v[148:151], off offset:256
	s_branch .LBB0_1112
.Lmrg_fin_A:
	global_load_dwordx4 v[158:161], v[152:153], off
	global_load_dwordx4 v[162:165], v[154:155], off
	global_load_dwordx4 v[176:179], v[152:153], off offset:256
	global_load_dwordx4 v[180:183], v[154:155], off offset:256
	v_ashrrev_i32_e32 v147, 31, v146
	v_lshlrev_b64 v[150:151], 11, v[146:147]
	v_lshl_add_u64 v[150:151], s[10:11], 0, v[150:151]
	s_cmp_lg_u32 s7, 2
	s_waitcnt vmcnt(2)
	v_lshlrev_b32_e32 v147, 16, v158
	v_and_b32_e32 v166, 0xffff0000, v158
	v_lshlrev_b32_e32 v167, 16, v159
	v_and_b32_e32 v168, 0xffff0000, v159
	v_lshlrev_b32_e32 v169, 16, v160
	v_and_b32_e32 v170, 0xffff0000, v160
	v_lshlrev_b32_e32 v171, 16, v161
	v_and_b32_e32 v172, 0xffff0000, v161
	v_mov_b32_e32 v158, v147
	v_mov_b32_e32 v159, v166
	v_mov_b32_e32 v160, v167
	v_mov_b32_e32 v161, v168
	v_mov_b32_e32 v162, v169
	v_mov_b32_e32 v163, v170
	v_mov_b32_e32 v164, v171
	v_mov_b32_e32 v165, v172
	v_pk_mul_f32 v[112:113], v[112:113], v[160:161]
	v_pk_mul_f32 v[110:111], v[110:111], v[158:159]
	v_pk_mul_f32 v[108:109], v[108:109], v[164:165]
	v_pk_mul_f32 v[106:107], v[106:107], v[162:163]
	s_waitcnt vmcnt(0)
	s_cbranch_scc1 .LBB0_1082_A
	v_lshl_add_u64 v[162:163], v[144:145], 1, v[150:151]
	v_cvt_pk_bf16_f32 v158, v110, v111
	v_cvt_pk_bf16_f32 v159, v112, v113
	v_cvt_pk_bf16_f32 v160, v106, v107
	v_cvt_pk_bf16_f32 v161, v108, v109
	global_store_dwordx4 v[162:163], v[158:161], off
.LBB0_1082_A:
	v_cndmask_b32_e64 v147, 0, 1, s[30:31]
	v_cmp_ne_u32_e64 s[6:7], 1, v147
	s_andn2_b64 vcc, exec, s[30:31]
	v_lshlrev_b32_e32 v147, 16, v176
	v_and_b32_e32 v176, 0xffff0000, v176
	v_lshlrev_b32_e32 v162, 16, v177
	v_and_b32_e32 v177, 0xffff0000, v177
	v_lshlrev_b32_e32 v165, 16, v178
	v_and_b32_e32 v178, 0xffff0000, v178
	v_lshlrev_b32_e32 v166, 16, v179
	v_and_b32_e32 v179, 0xffff0000, v179
	v_mov_b32_e32 v180, v147
	v_mov_b32_e32 v181, v176
	v_mov_b32_e32 v182, v162
	v_mov_b32_e32 v183, v177
	v_mov_b32_e32 v176, v165
	v_mov_b32_e32 v177, v178
	v_mov_b32_e32 v178, v166
	v_mov_b32_e32 v179, v179
	v_pk_mul_f32 v[80:81], v[80:81], v[182:183]
	v_pk_mul_f32 v[78:79], v[78:79], v[180:181]
	v_pk_mul_f32 v[76:77], v[76:77], v[178:179]
	v_pk_mul_f32 v[74:75], v[74:75], v[176:177]
	s_cbranch_vccnz .LBB0_1084_A
	v_lshl_add_u64 v[150:151], v[144:145], 1, v[150:151]
	v_cvt_pk_bf16_f32 v180, v78, v79
	v_cvt_pk_bf16_f32 v181, v80, v81
	v_cvt_pk_bf16_f32 v182, v74, v75
	v_cvt_pk_bf16_f32 v183, v76, v77
	global_store_dwordx4 v[150:151], v[180:183], off offset:256
.LBB0_1084_A:
	v_or_b32_e32 v150, 16, v146
	s_nop 0
	v_mov_b64_e32 v[152:153], s[8:9]
	v_mad_i64_i32 v[152:153], s[38:39], v150, s85, v[152:153]
	v_lshl_add_u64 v[154:155], v[152:153], 0, s[88:89]
	v_lshl_add_u64 v[152:153], s[34:35], 1, v[154:155]
	v_lshl_add_u64 v[154:155], s[36:37], 1, v[154:155]
	v_lshl_add_u64 v[152:153], v[152:153], 0, v[148:149]
	v_lshl_add_u64 v[154:155], v[154:155], 0, v[148:149]
	global_load_dwordx4 v[158:161], v[152:153], off
	global_load_dwordx4 v[162:165], v[154:155], off
	global_load_dwordx4 v[176:179], v[152:153], off offset:256
	global_load_dwordx4 v[180:183], v[154:155], off offset:256
	v_ashrrev_i32_e32 v151, 31, v150
	v_lshlrev_b64 v[150:151], 11, v[150:151]
	s_and_b64 vcc, exec, s[6:7]
	v_lshl_add_u64 v[150:151], s[10:11], 0, v[150:151]
	s_waitcnt vmcnt(3)
	v_lshlrev_b32_e32 v147, 16, v158
	v_and_b32_e32 v166, 0xffff0000, v158
	v_lshlrev_b32_e32 v167, 16, v159
	v_and_b32_e32 v168, 0xffff0000, v159
	s_waitcnt vmcnt(2)
	v_lshlrev_b32_e32 v169, 16, v160
	v_and_b32_e32 v170, 0xffff0000, v160
	v_lshlrev_b32_e32 v171, 16, v161
	v_and_b32_e32 v172, 0xffff0000, v161
	v_mov_b32_e32 v158, v147
	v_mov_b32_e32 v159, v166
	v_mov_b32_e32 v160, v167
	v_mov_b32_e32 v161, v168
	v_mov_b32_e32 v162, v169
	v_mov_b32_e32 v163, v170
	v_mov_b32_e32 v164, v171
	v_mov_b32_e32 v165, v172
	v_pk_mul_f32 v[104:105], v[104:105], v[160:161]
	v_pk_mul_f32 v[102:103], v[102:103], v[158:159]
	v_pk_mul_f32 v[100:101], v[100:101], v[164:165]
	v_pk_mul_f32 v[98:99], v[98:99], v[162:163]
	s_waitcnt vmcnt(0)
	s_cbranch_vccnz .LBB0_1086_A
	v_lshl_add_u64 v[162:163], v[144:145], 1, v[150:151]
	v_cvt_pk_bf16_f32 v158, v102, v103
	v_cvt_pk_bf16_f32 v159, v104, v105
	v_cvt_pk_bf16_f32 v160, v98, v99
	v_cvt_pk_bf16_f32 v161, v100, v101
	global_store_dwordx4 v[162:163], v[158:161], off
.LBB0_1086_A:
	s_and_b64 vcc, exec, s[6:7]
	v_lshlrev_b32_e32 v147, 16, v176
	v_and_b32_e32 v176, 0xffff0000, v176
	v_lshlrev_b32_e32 v162, 16, v177
	v_and_b32_e32 v177, 0xffff0000, v177
	v_lshlrev_b32_e32 v165, 16, v178
	v_and_b32_e32 v178, 0xffff0000, v178
	v_lshlrev_b32_e32 v166, 16, v179
	v_and_b32_e32 v179, 0xffff0000, v179
	v_mov_b32_e32 v180, v147
	v_mov_b32_e32 v181, v176
	v_mov_b32_e32 v182, v162
	v_mov_b32_e32 v183, v177
	v_mov_b32_e32 v176, v165
	v_mov_b32_e32 v177, v178
	v_mov_b32_e32 v178, v166
	v_mov_b32_e32 v179, v179
	v_pk_mul_f32 v[72:73], v[72:73], v[182:183]
	v_pk_mul_f32 v[70:71], v[70:71], v[180:181]
	v_pk_mul_f32 v[68:69], v[68:69], v[178:179]
	v_pk_mul_f32 v[66:67], v[66:67], v[176:177]
	s_cbranch_vccnz .LBB0_1088_A
	v_lshl_add_u64 v[150:151], v[144:145], 1, v[150:151]
	v_cvt_pk_bf16_f32 v180, v70, v71
	v_cvt_pk_bf16_f32 v181, v72, v73
	v_cvt_pk_bf16_f32 v182, v66, v67
	v_cvt_pk_bf16_f32 v183, v68, v69
	global_store_dwordx4 v[150:151], v[180:183], off offset:256
.LBB0_1088_A:
	v_or_b32_e32 v150, 32, v146
	s_nop 0
	v_mov_b64_e32 v[152:153], s[8:9]
	v_mad_i64_i32 v[152:153], s[38:39], v150, s85, v[152:153]
	v_lshl_add_u64 v[154:155], v[152:153], 0, s[88:89]
	v_lshl_add_u64 v[152:153], s[34:35], 1, v[154:155]
	v_lshl_add_u64 v[154:155], s[36:37], 1, v[154:155]
	v_lshl_add_u64 v[152:153], v[152:153], 0, v[148:149]
	v_lshl_add_u64 v[154:155], v[154:155], 0, v[148:149]
	global_load_dwordx4 v[158:161], v[152:153], off
	global_load_dwordx4 v[162:165], v[154:155], off
	global_load_dwordx4 v[176:179], v[152:153], off offset:256
	global_load_dwordx4 v[180:183], v[154:155], off offset:256
	v_ashrrev_i32_e32 v151, 31, v150
	v_lshlrev_b64 v[150:151], 11, v[150:151]
	s_and_b64 vcc, exec, s[6:7]
	v_lshl_add_u64 v[150:151], s[10:11], 0, v[150:151]
	s_waitcnt vmcnt(3)
	v_lshlrev_b32_e32 v147, 16, v158
	v_and_b32_e32 v166, 0xffff0000, v158
	v_lshlrev_b32_e32 v167, 16, v159
	v_and_b32_e32 v168, 0xffff0000, v159
	s_waitcnt vmcnt(2)
	v_lshlrev_b32_e32 v169, 16, v160
	v_and_b32_e32 v170, 0xffff0000, v160
	v_lshlrev_b32_e32 v171, 16, v161
	v_and_b32_e32 v172, 0xffff0000, v161
	v_mov_b32_e32 v158, v147
	v_mov_b32_e32 v159, v166
	v_mov_b32_e32 v160, v167
	v_mov_b32_e32 v161, v168
	v_mov_b32_e32 v162, v169
	v_mov_b32_e32 v163, v170
	v_mov_b32_e32 v164, v171
	v_mov_b32_e32 v165, v172
	v_pk_mul_f32 v[96:97], v[96:97], v[160:161]
	v_pk_mul_f32 v[94:95], v[94:95], v[158:159]
	v_pk_mul_f32 v[92:93], v[92:93], v[164:165]
	v_pk_mul_f32 v[90:91], v[90:91], v[162:163]
	s_waitcnt vmcnt(0)
	s_cbranch_vccnz .LBB0_1090_A
	v_lshl_add_u64 v[162:163], v[144:145], 1, v[150:151]
	v_cvt_pk_bf16_f32 v158, v94, v95
	v_cvt_pk_bf16_f32 v159, v96, v97
	v_cvt_pk_bf16_f32 v160, v90, v91
	v_cvt_pk_bf16_f32 v161, v92, v93
	global_store_dwordx4 v[162:163], v[158:161], off
.LBB0_1090_A:
	s_and_b64 vcc, exec, s[6:7]
	v_lshlrev_b32_e32 v147, 16, v176
	v_and_b32_e32 v176, 0xffff0000, v176
	v_lshlrev_b32_e32 v162, 16, v177
	v_and_b32_e32 v177, 0xffff0000, v177
	v_lshlrev_b32_e32 v165, 16, v178
	v_and_b32_e32 v178, 0xffff0000, v178
	v_lshlrev_b32_e32 v166, 16, v179
	v_and_b32_e32 v179, 0xffff0000, v179
	v_mov_b32_e32 v180, v147
	v_mov_b32_e32 v181, v176
	v_mov_b32_e32 v182, v162
	v_mov_b32_e32 v183, v177
	v_mov_b32_e32 v176, v165
	v_mov_b32_e32 v177, v178
	v_mov_b32_e32 v178, v166
	v_mov_b32_e32 v179, v179
	v_pk_mul_f32 v[64:65], v[64:65], v[182:183]
	v_pk_mul_f32 v[62:63], v[62:63], v[180:181]
	v_pk_mul_f32 v[60:61], v[60:61], v[178:179]
	v_pk_mul_f32 v[58:59], v[58:59], v[176:177]
	s_cbranch_vccnz .LBB0_1092_A
	v_lshl_add_u64 v[150:151], v[144:145], 1, v[150:151]
	v_cvt_pk_bf16_f32 v180, v62, v63
	v_cvt_pk_bf16_f32 v181, v64, v65
	v_cvt_pk_bf16_f32 v182, v58, v59
	v_cvt_pk_bf16_f32 v183, v60, v61
	global_store_dwordx4 v[150:151], v[180:183], off offset:256
.LBB0_1092_A:
	v_or_b32_e32 v150, 48, v146
	s_nop 0
	v_mov_b64_e32 v[152:153], s[8:9]
	v_mad_i64_i32 v[152:153], s[38:39], v150, s85, v[152:153]
	v_lshl_add_u64 v[154:155], v[152:153], 0, s[88:89]
	v_lshl_add_u64 v[152:153], s[34:35], 1, v[154:155]
	v_lshl_add_u64 v[154:155], s[36:37], 1, v[154:155]
	v_lshl_add_u64 v[152:153], v[152:153], 0, v[148:149]
	v_lshl_add_u64 v[154:155], v[154:155], 0, v[148:149]
	global_load_dwordx4 v[158:161], v[152:153], off
	global_load_dwordx4 v[162:165], v[154:155], off
	global_load_dwordx4 v[176:179], v[152:153], off offset:256
	global_load_dwordx4 v[180:183], v[154:155], off offset:256
	v_ashrrev_i32_e32 v151, 31, v150
	v_lshlrev_b64 v[150:151], 11, v[150:151]
	s_and_b64 vcc, exec, s[6:7]
	v_lshl_add_u64 v[150:151], s[10:11], 0, v[150:151]
	s_waitcnt vmcnt(3)
	v_lshlrev_b32_e32 v147, 16, v158
	v_and_b32_e32 v166, 0xffff0000, v158
	v_lshlrev_b32_e32 v167, 16, v159
	v_and_b32_e32 v168, 0xffff0000, v159
	s_waitcnt vmcnt(2)
	v_lshlrev_b32_e32 v169, 16, v160
	v_and_b32_e32 v170, 0xffff0000, v160
	v_lshlrev_b32_e32 v171, 16, v161
	v_and_b32_e32 v172, 0xffff0000, v161
	v_mov_b32_e32 v158, v147
	v_mov_b32_e32 v159, v166
	v_mov_b32_e32 v160, v167
	v_mov_b32_e32 v161, v168
	v_mov_b32_e32 v162, v169
	v_mov_b32_e32 v163, v170
	v_mov_b32_e32 v164, v171
	v_mov_b32_e32 v165, v172
	v_pk_mul_f32 v[88:89], v[88:89], v[160:161]
	v_pk_mul_f32 v[86:87], v[86:87], v[158:159]
	v_pk_mul_f32 v[84:85], v[84:85], v[164:165]
	v_pk_mul_f32 v[82:83], v[82:83], v[162:163]
	s_waitcnt vmcnt(0)
	s_cbranch_vccnz .LBB0_1094_A
	v_lshl_add_u64 v[162:163], v[144:145], 1, v[150:151]
	v_cvt_pk_bf16_f32 v158, v86, v87
	v_cvt_pk_bf16_f32 v159, v88, v89
	v_cvt_pk_bf16_f32 v160, v82, v83
	v_cvt_pk_bf16_f32 v161, v84, v85
	global_store_dwordx4 v[162:163], v[158:161], off
.LBB0_1094_A:
	s_and_b64 vcc, exec, s[6:7]
	v_lshlrev_b32_e32 v147, 16, v176
	v_and_b32_e32 v176, 0xffff0000, v176
	v_lshlrev_b32_e32 v162, 16, v177
	v_and_b32_e32 v177, 0xffff0000, v177
	v_lshlrev_b32_e32 v165, 16, v178
	v_and_b32_e32 v178, 0xffff0000, v178
	v_lshlrev_b32_e32 v166, 16, v179
	v_and_b32_e32 v179, 0xffff0000, v179
	v_mov_b32_e32 v180, v147
	v_mov_b32_e32 v181, v176
	v_mov_b32_e32 v182, v162
	v_mov_b32_e32 v183, v177
	v_mov_b32_e32 v176, v165
	v_mov_b32_e32 v177, v178
	v_mov_b32_e32 v178, v166
	v_mov_b32_e32 v179, v179
	v_pk_mul_f32 v[56:57], v[56:57], v[182:183]
	v_pk_mul_f32 v[54:55], v[54:55], v[180:181]
	v_pk_mul_f32 v[52:53], v[52:53], v[178:179]
	v_pk_mul_f32 v[50:51], v[50:51], v[176:177]
	s_cbranch_vccnz .LBB0_1096_A
	v_lshl_add_u64 v[150:151], v[144:145], 1, v[150:151]
	v_cvt_pk_bf16_f32 v180, v54, v55
	v_cvt_pk_bf16_f32 v181, v56, v57
	v_cvt_pk_bf16_f32 v182, v50, v51
	v_cvt_pk_bf16_f32 v183, v52, v53
	global_store_dwordx4 v[150:151], v[180:183], off offset:256
.LBB0_1096_A:
	v_add_u32_e32 v150, 0x80, v146
	s_nop 0
	v_mov_b64_e32 v[152:153], s[8:9]
	v_mad_i64_i32 v[152:153], s[38:39], v150, s85, v[152:153]
	v_lshl_add_u64 v[154:155], v[152:153], 0, s[88:89]
	v_lshl_add_u64 v[152:153], s[34:35], 1, v[154:155]
	v_lshl_add_u64 v[154:155], s[36:37], 1, v[154:155]
	v_lshl_add_u64 v[152:153], v[152:153], 0, v[148:149]
	v_lshl_add_u64 v[154:155], v[154:155], 0, v[148:149]
	global_load_dwordx4 v[158:161], v[152:153], off
	global_load_dwordx4 v[162:165], v[154:155], off
	global_load_dwordx4 v[176:179], v[152:153], off offset:256
	global_load_dwordx4 v[180:183], v[154:155], off offset:256
	v_ashrrev_i32_e32 v151, 31, v150
	v_lshlrev_b64 v[150:151], 11, v[150:151]
	s_and_b64 vcc, exec, s[6:7]
	v_lshl_add_u64 v[150:151], s[10:11], 0, v[150:151]
	s_waitcnt vmcnt(3)
	v_lshlrev_b32_e32 v147, 16, v158
	v_and_b32_e32 v166, 0xffff0000, v158
	v_lshlrev_b32_e32 v167, 16, v159
	v_and_b32_e32 v168, 0xffff0000, v159
	s_waitcnt vmcnt(2)
	v_lshlrev_b32_e32 v169, 16, v160
	v_and_b32_e32 v170, 0xffff0000, v160
	v_lshlrev_b32_e32 v171, 16, v161
	v_and_b32_e32 v172, 0xffff0000, v161
	v_mov_b32_e32 v158, v147
	v_mov_b32_e32 v159, v166
	v_mov_b32_e32 v160, v167
	v_mov_b32_e32 v161, v168
	v_mov_b32_e32 v162, v169
	v_mov_b32_e32 v163, v170
	v_mov_b32_e32 v164, v171
	v_mov_b32_e32 v165, v172
	v_pk_mul_f32 v[48:49], v[48:49], v[160:161]
	v_pk_mul_f32 v[46:47], v[46:47], v[158:159]
	v_pk_mul_f32 v[44:45], v[44:45], v[164:165]
	v_pk_mul_f32 v[42:43], v[42:43], v[162:163]
	s_waitcnt vmcnt(0)
	s_cbranch_vccnz .LBB0_1098_A
	v_lshl_add_u64 v[162:163], v[144:145], 1, v[150:151]
	v_cvt_pk_bf16_f32 v158, v46, v47
	v_cvt_pk_bf16_f32 v159, v48, v49
	v_cvt_pk_bf16_f32 v160, v42, v43
	v_cvt_pk_bf16_f32 v161, v44, v45
	global_store_dwordx4 v[162:163], v[158:161], off
.LBB0_1098_A:
	s_and_b64 vcc, exec, s[6:7]
	v_lshlrev_b32_e32 v147, 16, v176
	v_and_b32_e32 v176, 0xffff0000, v176
	v_lshlrev_b32_e32 v162, 16, v177
	v_and_b32_e32 v177, 0xffff0000, v177
	v_lshlrev_b32_e32 v165, 16, v178
	v_and_b32_e32 v178, 0xffff0000, v178
	v_lshlrev_b32_e32 v166, 16, v179
	v_and_b32_e32 v179, 0xffff0000, v179
	v_mov_b32_e32 v180, v147
	v_mov_b32_e32 v181, v176
	v_mov_b32_e32 v182, v162
	v_mov_b32_e32 v183, v177
	v_mov_b32_e32 v176, v165
	v_mov_b32_e32 v177, v178
	v_mov_b32_e32 v178, v166
	v_mov_b32_e32 v179, v179
	v_pk_mul_f32 v[16:17], v[16:17], v[182:183]
	v_pk_mul_f32 v[14:15], v[14:15], v[180:181]
	v_pk_mul_f32 v[12:13], v[12:13], v[178:179]
	v_pk_mul_f32 v[10:11], v[10:11], v[176:177]
	s_cbranch_vccnz .LBB0_1100_A
	v_lshl_add_u64 v[150:151], v[144:145], 1, v[150:151]
	v_cvt_pk_bf16_f32 v180, v14, v15
	v_cvt_pk_bf16_f32 v181, v16, v17
	v_cvt_pk_bf16_f32 v182, v10, v11
	v_cvt_pk_bf16_f32 v183, v12, v13
	global_store_dwordx4 v[150:151], v[180:183], off offset:256
.LBB0_1100_A:
	v_add_u32_e32 v150, 0x90, v146
	s_nop 0
	v_mov_b64_e32 v[152:153], s[8:9]
	v_mad_i64_i32 v[152:153], s[38:39], v150, s85, v[152:153]
	v_lshl_add_u64 v[154:155], v[152:153], 0, s[88:89]
	v_lshl_add_u64 v[152:153], s[34:35], 1, v[154:155]
	v_lshl_add_u64 v[154:155], s[36:37], 1, v[154:155]
	v_lshl_add_u64 v[152:153], v[152:153], 0, v[148:149]
	v_lshl_add_u64 v[154:155], v[154:155], 0, v[148:149]
	global_load_dwordx4 v[158:161], v[152:153], off
	global_load_dwordx4 v[162:165], v[154:155], off
	global_load_dwordx4 v[176:179], v[152:153], off offset:256
	global_load_dwordx4 v[180:183], v[154:155], off offset:256
	v_ashrrev_i32_e32 v151, 31, v150
	v_lshlrev_b64 v[150:151], 11, v[150:151]
	s_and_b64 vcc, exec, s[6:7]
	v_lshl_add_u64 v[150:151], s[10:11], 0, v[150:151]
	s_waitcnt vmcnt(3)
	v_lshlrev_b32_e32 v147, 16, v158
	v_and_b32_e32 v166, 0xffff0000, v158
	v_lshlrev_b32_e32 v167, 16, v159
	v_and_b32_e32 v168, 0xffff0000, v159
	s_waitcnt vmcnt(2)
	v_lshlrev_b32_e32 v169, 16, v160
	v_and_b32_e32 v170, 0xffff0000, v160
	v_lshlrev_b32_e32 v171, 16, v161
	v_and_b32_e32 v172, 0xffff0000, v161
	v_mov_b32_e32 v158, v147
	v_mov_b32_e32 v159, v166
	v_mov_b32_e32 v160, v167
	v_mov_b32_e32 v161, v168
	v_mov_b32_e32 v162, v169
	v_mov_b32_e32 v163, v170
	v_mov_b32_e32 v164, v171
	v_mov_b32_e32 v165, v172
	v_pk_mul_f32 v[40:41], v[40:41], v[160:161]
	v_pk_mul_f32 v[38:39], v[38:39], v[158:159]
	v_pk_mul_f32 v[36:37], v[36:37], v[164:165]
	v_pk_mul_f32 v[34:35], v[34:35], v[162:163]
	s_waitcnt vmcnt(0)
	s_cbranch_vccnz .LBB0_1102_A
	v_lshl_add_u64 v[162:163], v[144:145], 1, v[150:151]
	v_cvt_pk_bf16_f32 v158, v38, v39
	v_cvt_pk_bf16_f32 v159, v40, v41
	v_cvt_pk_bf16_f32 v160, v34, v35
	v_cvt_pk_bf16_f32 v161, v36, v37
	global_store_dwordx4 v[162:163], v[158:161], off
.LBB0_1102_A:
	s_and_b64 vcc, exec, s[6:7]
	v_lshlrev_b32_e32 v147, 16, v176
	v_and_b32_e32 v176, 0xffff0000, v176
	v_lshlrev_b32_e32 v162, 16, v177
	v_and_b32_e32 v177, 0xffff0000, v177
	v_lshlrev_b32_e32 v165, 16, v178
	v_and_b32_e32 v178, 0xffff0000, v178
	v_lshlrev_b32_e32 v166, 16, v179
	v_and_b32_e32 v179, 0xffff0000, v179
	v_mov_b32_e32 v180, v147
	v_mov_b32_e32 v181, v176
	v_mov_b32_e32 v182, v162
	v_mov_b32_e32 v183, v177
	v_mov_b32_e32 v176, v165
	v_mov_b32_e32 v177, v178
	v_mov_b32_e32 v178, v166
	v_mov_b32_e32 v179, v179
	v_pk_mul_f32 v[8:9], v[8:9], v[182:183]
	v_pk_mul_f32 v[6:7], v[6:7], v[180:181]
	v_pk_mul_f32 v[4:5], v[4:5], v[178:179]
	v_pk_mul_f32 v[2:3], v[2:3], v[176:177]
	s_cbranch_vccnz .LBB0_1104_A
	v_lshl_add_u64 v[150:151], v[144:145], 1, v[150:151]
	v_cvt_pk_bf16_f32 v180, v6, v7
	v_cvt_pk_bf16_f32 v181, v8, v9
	v_cvt_pk_bf16_f32 v182, v2, v3
	v_cvt_pk_bf16_f32 v183, v4, v5
	global_store_dwordx4 v[150:151], v[180:183], off offset:256
.LBB0_1104_A:
	v_add_u32_e32 v150, 0xa0, v146
	s_nop 0
	v_mov_b64_e32 v[152:153], s[8:9]
	v_mad_i64_i32 v[152:153], s[38:39], v150, s85, v[152:153]
	v_lshl_add_u64 v[154:155], v[152:153], 0, s[88:89]
	v_lshl_add_u64 v[152:153], s[34:35], 1, v[154:155]
	v_lshl_add_u64 v[154:155], s[36:37], 1, v[154:155]
	v_lshl_add_u64 v[152:153], v[152:153], 0, v[148:149]
	v_lshl_add_u64 v[154:155], v[154:155], 0, v[148:149]
	global_load_dwordx4 v[158:161], v[152:153], off
	global_load_dwordx4 v[162:165], v[154:155], off
	global_load_dwordx4 v[176:179], v[152:153], off offset:256
	global_load_dwordx4 v[180:183], v[154:155], off offset:256
	v_ashrrev_i32_e32 v151, 31, v150
	v_lshlrev_b64 v[150:151], 11, v[150:151]
	s_and_b64 vcc, exec, s[6:7]
	v_lshl_add_u64 v[150:151], s[10:11], 0, v[150:151]
	s_waitcnt vmcnt(3)
	v_lshlrev_b32_e32 v147, 16, v158
	v_and_b32_e32 v166, 0xffff0000, v158
	v_lshlrev_b32_e32 v167, 16, v159
	v_and_b32_e32 v168, 0xffff0000, v159
	s_waitcnt vmcnt(2)
	v_lshlrev_b32_e32 v169, 16, v160
	v_and_b32_e32 v170, 0xffff0000, v160
	v_lshlrev_b32_e32 v171, 16, v161
	v_and_b32_e32 v172, 0xffff0000, v161
	v_mov_b32_e32 v158, v147
	v_mov_b32_e32 v159, v166
	v_mov_b32_e32 v160, v167
	v_mov_b32_e32 v161, v168
	v_mov_b32_e32 v162, v169
	v_mov_b32_e32 v163, v170
	v_mov_b32_e32 v164, v171
	v_mov_b32_e32 v165, v172
	v_pk_mul_f32 v[32:33], v[32:33], v[160:161]
	v_pk_mul_f32 v[30:31], v[30:31], v[158:159]
	v_pk_mul_f32 v[28:29], v[28:29], v[164:165]
	v_pk_mul_f32 v[26:27], v[26:27], v[162:163]
	s_waitcnt vmcnt(0)
	s_cbranch_vccnz .LBB0_1106_A
	v_lshl_add_u64 v[162:163], v[144:145], 1, v[150:151]
	v_cvt_pk_bf16_f32 v158, v30, v31
	v_cvt_pk_bf16_f32 v159, v32, v33
	v_cvt_pk_bf16_f32 v160, v26, v27
	v_cvt_pk_bf16_f32 v161, v28, v29
	global_store_dwordx4 v[162:163], v[158:161], off
.LBB0_1106_A:
	s_and_b64 vcc, exec, s[6:7]
	v_lshlrev_b32_e32 v147, 16, v176
	v_and_b32_e32 v176, 0xffff0000, v176
	v_lshlrev_b32_e32 v162, 16, v177
	v_and_b32_e32 v177, 0xffff0000, v177
	v_lshlrev_b32_e32 v165, 16, v178
	v_and_b32_e32 v178, 0xffff0000, v178
	v_lshlrev_b32_e32 v166, 16, v179
	v_and_b32_e32 v179, 0xffff0000, v179
	v_mov_b32_e32 v180, v147
	v_mov_b32_e32 v181, v176
	v_mov_b32_e32 v182, v162
	v_mov_b32_e32 v183, v177
	v_mov_b32_e32 v176, v165
	v_mov_b32_e32 v177, v178
	v_mov_b32_e32 v178, v166
	v_mov_b32_e32 v179, v179
	v_pk_mul_f32 v[116:117], v[116:117], v[182:183]
	v_pk_mul_f32 v[114:115], v[114:115], v[180:181]
	v_pk_mul_f32 v[120:121], v[120:121], v[178:179]
	v_pk_mul_f32 v[118:119], v[118:119], v[176:177]
	s_cbranch_vccnz .LBB0_1108_A
	v_lshl_add_u64 v[150:151], v[144:145], 1, v[150:151]
	v_cvt_pk_bf16_f32 v180, v114, v115
	v_cvt_pk_bf16_f32 v181, v116, v117
	v_cvt_pk_bf16_f32 v182, v118, v119
	v_cvt_pk_bf16_f32 v183, v120, v121
	global_store_dwordx4 v[150:151], v[180:183], off offset:256
.LBB0_1108_A:
	v_add_u32_e32 v146, 0xb0, v146
	v_mov_b64_e32 v[150:151], s[8:9]
	v_mad_i64_i32 v[150:151], s[38:39], v146, s85, v[150:151]
	v_lshl_add_u64 v[158:159], v[150:151], 0, s[88:89]
	v_lshl_add_u64 v[150:151], s[34:35], 1, v[158:159]
	v_lshl_add_u64 v[158:159], s[36:37], 1, v[158:159]
	v_lshl_add_u64 v[150:151], v[150:151], 0, v[148:149]
	v_lshl_add_u64 v[148:149], v[158:159], 0, v[148:149]
	global_load_dwordx4 v[152:155], v[150:151], off
	global_load_dwordx4 v[158:161], v[148:149], off
	v_ashrrev_i32_e32 v147, 31, v146
	v_lshlrev_b64 v[146:147], 11, v[146:147]
	s_and_b64 vcc, exec, s[6:7]
	v_lshl_add_u64 v[146:147], s[10:11], 0, v[146:147]
	s_waitcnt vmcnt(1)
	v_lshlrev_b32_e32 v162, 16, v152
	v_and_b32_e32 v163, 0xffff0000, v152
	v_lshlrev_b32_e32 v164, 16, v153
	v_and_b32_e32 v165, 0xffff0000, v153
	s_waitcnt vmcnt(0)
	v_lshlrev_b32_e32 v166, 16, v154
	v_and_b32_e32 v167, 0xffff0000, v154
	v_lshlrev_b32_e32 v168, 16, v155
	v_and_b32_e32 v169, 0xffff0000, v155
	v_mov_b32_e32 v152, v162
	v_mov_b32_e32 v153, v163
	v_mov_b32_e32 v154, v164
	v_mov_b32_e32 v155, v165
	v_mov_b32_e32 v158, v166
	v_mov_b32_e32 v159, v167
	v_mov_b32_e32 v160, v168
	v_mov_b32_e32 v161, v169
	v_pk_mul_f32 v[24:25], v[24:25], v[154:155]
	v_pk_mul_f32 v[22:23], v[22:23], v[152:153]
	v_pk_mul_f32 v[20:21], v[20:21], v[160:161]
	v_pk_mul_f32 v[18:19], v[18:19], v[158:159]
	s_cbranch_vccnz .LBB0_1110_A
	v_lshl_add_u64 v[158:159], v[144:145], 1, v[146:147]
	v_cvt_pk_bf16_f32 v152, v22, v23
	v_cvt_pk_bf16_f32 v153, v24, v25
	v_cvt_pk_bf16_f32 v154, v18, v19
	v_cvt_pk_bf16_f32 v155, v20, v21
	global_store_dwordx4 v[158:159], v[152:155], off
.LBB0_1110_A:
	global_load_dwordx4 v[150:153], v[150:151], off offset:256
	s_nop 0
	global_load_dwordx4 v[158:161], v[148:149], off offset:256
	s_and_b64 vcc, exec, s[6:7]
	s_waitcnt vmcnt(1)
	v_lshlrev_b32_e32 v162, 16, v152
	s_waitcnt vmcnt(0)
	v_and_b32_e32 v163, 0xffff0000, v152
	v_lshlrev_b32_e32 v164, 16, v153
	v_and_b32_e32 v165, 0xffff0000, v153
	v_lshlrev_b32_e32 v148, 16, v150
	v_and_b32_e32 v149, 0xffff0000, v150
	v_lshlrev_b32_e32 v150, 16, v151
	v_and_b32_e32 v151, 0xffff0000, v151
	v_mov_b32_e32 v148, v148
	v_mov_b32_e32 v149, v149
	v_mov_b32_e32 v150, v150
	v_mov_b32_e32 v151, v151
	v_mov_b32_e32 v152, v162
	v_mov_b32_e32 v153, v163
	v_mov_b32_e32 v154, v164
	v_mov_b32_e32 v155, v165
	v_pk_mul_f32 v[124:125], v[124:125], v[150:151]
	v_pk_mul_f32 v[122:123], v[122:123], v[148:149]
	v_pk_mul_f32 v[128:129], v[128:129], v[154:155]
	v_pk_mul_f32 v[126:127], v[126:127], v[152:153]
	s_cbranch_vccnz .LBB0_1112
	v_lshl_add_u64 v[144:145], v[144:145], 1, v[146:147]
	v_cvt_pk_bf16_f32 v148, v122, v123
	v_cvt_pk_bf16_f32 v149, v124, v125
	v_cvt_pk_bf16_f32 v150, v126, v127
	v_cvt_pk_bf16_f32 v151, v128, v129
	global_store_dwordx4 v[144:145], v[148:151], off offset:256
